# MoE1/MoE2 k-loops rotated: last 8 MFMAs of a step issued after next barrier, counted lgkmcnt
# speedup vs baseline: 1.0168x; 1.0168x over previous
; __device__ __forceinline__ int trow(int j) { const int t = otid(); return ((t >> 6) * 2 + j) * 16 + ((t & 63) >> 2); }
; __device__ __forceinline__ int tkc() { const int l = otid() & 63; return ((l & 3) ^ ((0 - (l >> 4)) & 3)) * 8; }
; __device__ __forceinline__ void zero_acc(f32x4 (&acc)[8][4]) {
; #pragma unroll
;   for (int i = 0; i < 8; ++i)
; #pragma unroll
;     for (int j = 0; j < 4; ++j) acc[i][j] = (f32x4){0.f, 0.f, 0.f, 0.f};
; __device__ __forceinline__ TP moe1_ptrs(const Params& p, int e, int mt, int nt) {
;   const u16* X = (const u16*)(p.ws + OFF_ACT1);
;   const int* idx = (const int*)(p.ws + OFF_IDX);
;   TP t;
;   {
;     const int r0 = mt * 256 + trow(0), r1 = mt * 256 + trow(1);
;     t.a0 = X + (size_t)((r0 >> 8) * 2048 + idx[e * 8192 + r0]) * 1024 + tkc();
;     t.a1 = X + (size_t)((r1 >> 8) * 2048 + idx[e * 8192 + r1]) * 1024 + tkc();
;   }
;   {
;     const int R0 = trow(0), R1 = trow(1);
;     const int P0 = (R0 & ~63) | (((R0 >> 2) & 3) * 16 + ((R0 >> 4) & 3) * 4 + (R0 & 3));
;     const int P1 = (R1 & ~63) | (((R1 >> 2) & 3) * 16 + ((R1 >> 4) & 3) * 4 + (R1 & 3));
;     const u16* wb = (const u16*)(p.ws + OFF_WGU) + (size_t)e * 5632 * 1024 + (size_t)(nt * 256) * 1024 + tkc();
;     t.b0 = wb + (size_t)P0 * 1024; t.b1 = wb + (size_t)P1 * 1024;
.LBB0_1299:
	s_mov_b32 s27, s26
	s_add_i32 s26, s26, s3
	s_cmpk_gt_i32 s26, 0x15ff
	s_cselect_b64 s[16:17], -1, 0
	s_cmpk_lt_i32 s26, 0x1600
	s_cselect_b64 s[18:19], -1, 0
	s_and_b64 s[20:21], s[18:19], exec
	s_cselect_b32 s20, s26, s27
	s_mul_hi_i32 s21, s20, 0x2e8ba2e9
	s_lshr_b32 s22, s21, 31
	s_ashr_i32 s21, s21, 7
	s_add_i32 s28, s21, s22
	s_mul_i32 s21, s28, 0x2c0
	s_sub_i32 s20, s20, s21
	s_bfe_u32 s21, s20, 0x5001a
	s_add_i32 s21, s20, s21
	s_sext_i32_i16 s22, s21
	s_and_b32 s21, s21, 0xffe0
	v_mov_b32_e32 v0, v153
	s_sub_i32 s20, s20, s21
	s_sext_i32_i16 s20, s20
	v_ashrrev_i32_e32 v1, 1, v0
	v_bfe_u32 v0, v0, 2, 4
	s_lshl_b32 s20, s20, 8
	v_and_or_b32 v0, v1, s38, v0
	v_add_u32_e32 v134, s20, v0
	v_mov_b32_e32 v0, v153
	s_add_i32 s28, s28, s52
	v_ashrrev_i32_e32 v1, 1, v0
	v_bfe_u32 v0, v0, 2, 4
	v_and_or_b32 v0, v1, s38, v0
	v_add_u32_e32 v0, s20, v0
	s_lshl_b32 s20, s28, 13
	v_or_b32_e32 v147, 16, v0
	v_add_u32_e32 v0, s20, v134
	v_ashrrev_i32_e32 v1, 31, v0
	v_lshl_add_u64 v[0:1], v[0:1], 2, s[58:59]
	global_load_dword v154, v[0:1], off
	v_add_u32_e32 v0, s20, v147
	v_ashrrev_i32_e32 v1, 31, v0
	v_mov_b32_e32 v144, v153
	v_lshl_add_u64 v[0:1], v[0:1], 2, s[58:59]
	global_load_dword v155, v[0:1], off
	v_mov_b32_e32 v146, v153
	v_mov_b32_e32 v151, v153
	v_mov_b32_e32 v145, v153
	v_mov_b32_e32 v149, v153
	v_mov_b32_e32 v0, v153
	s_lshr_b32 s29, s22, 5
	v_lshlrev_b32_e32 v3, 2, v0
	v_and_b32_e32 v3, 48, v3
	v_sub_u32_e32 v3, 0, v3
	v_and_b32_e32 v156, 15, v0
	v_lshlrev_b32_e32 v1, 5, v0
	v_lshlrev_b32_e32 v2, 4, v0
	v_bitop3_b32 v157, v0, 48, v3 bitop3:0x48
	v_ashrrev_i32_e32 v158, 1, v0
	v_lshlrev_b32_e32 v0, 6, v0
	v_and_b32_e32 v1, 0xfffff800, v1
	v_and_b32_e32 v2, 0x3f0, v2
	v_and_or_b32 v3, v158, s2, v156
	v_and_b32_e32 v159, 0x33c0, v0
	v_mov_b32_e32 v0, 0
	v_lshl_or_b32 v160, v3, 6, v157
	v_or_b32_e32 v161, v159, v157
	v_add3_u32 v162, 0, v1, v2
	v_lshl_add_u64 v[136:137], v[136:137], 0, s[42:43]
	v_lshl_add_u64 v[138:139], v[138:139], 0, s[42:43]
	v_lshl_add_u64 v[140:141], v[140:141], 0, s[42:43]
	v_lshl_add_u64 v[142:143], v[142:143], 0, s[42:43]
	s_mov_b32 s20, 0x18000
	v_mov_b32_e32 v1, v0
	v_mov_b32_e32 v2, v0
	v_mov_b32_e32 v3, v0
	v_mov_b32_e32 v4, v0
	v_mov_b32_e32 v5, v0
	v_mov_b32_e32 v6, v0
	v_mov_b32_e32 v7, v0
	v_mov_b32_e32 v8, v0
	v_mov_b32_e32 v9, v0
	v_mov_b32_e32 v10, v0
	v_mov_b32_e32 v11, v0
	v_mov_b32_e32 v12, v0
	v_mov_b32_e32 v13, v0
	v_mov_b32_e32 v14, v0
	v_mov_b32_e32 v15, v0
	v_mov_b32_e32 v16, v0
	v_mov_b32_e32 v17, v0
	v_mov_b32_e32 v18, v0
	v_mov_b32_e32 v19, v0
	v_mov_b32_e32 v20, v0
	v_mov_b32_e32 v21, v0
	v_mov_b32_e32 v22, v0
	v_mov_b32_e32 v23, v0
	v_mov_b32_e32 v24, v0
	v_mov_b32_e32 v25, v0
	v_mov_b32_e32 v26, v0
	v_mov_b32_e32 v27, v0
	v_mov_b32_e32 v28, v0
	v_mov_b32_e32 v29, v0
	v_mov_b32_e32 v30, v0
	v_mov_b32_e32 v31, v0
	v_mov_b32_e32 v32, v0
	v_mov_b32_e32 v33, v0
	v_mov_b32_e32 v34, v0
	v_mov_b32_e32 v35, v0
	v_mov_b32_e32 v36, v0
	v_mov_b32_e32 v37, v0
	v_mov_b32_e32 v38, v0
	v_mov_b32_e32 v39, v0
	v_mov_b32_e32 v40, v0
	v_mov_b32_e32 v41, v0
	v_mov_b32_e32 v42, v0
	v_mov_b32_e32 v43, v0
	v_mov_b32_e32 v44, v0
	v_mov_b32_e32 v45, v0
	v_mov_b32_e32 v46, v0
	v_mov_b32_e32 v47, v0
	v_mov_b32_e32 v48, v0
	v_mov_b32_e32 v49, v0
	v_mov_b32_e32 v50, v0
	v_mov_b32_e32 v51, v0
	v_mov_b32_e32 v52, v0
	v_mov_b32_e32 v53, v0
	v_mov_b32_e32 v54, v0
	v_mov_b32_e32 v55, v0
	v_mov_b32_e32 v56, v0
	v_mov_b32_e32 v57, v0
	v_mov_b32_e32 v58, v0
	v_mov_b32_e32 v59, v0
	v_mov_b32_e32 v60, v0
	v_mov_b32_e32 v61, v0
	v_mov_b32_e32 v62, v0
	v_mov_b32_e32 v63, v0
	v_mov_b32_e32 v64, v0
	v_mov_b32_e32 v65, v0
	v_mov_b32_e32 v66, v0
	v_mov_b32_e32 v67, v0
	v_mov_b32_e32 v68, v0
	v_mov_b32_e32 v69, v0
	v_mov_b32_e32 v70, v0
	v_mov_b32_e32 v71, v0
	v_mov_b32_e32 v72, v0
	v_mov_b32_e32 v73, v0
	v_mov_b32_e32 v74, v0
	v_mov_b32_e32 v75, v0
	v_mov_b32_e32 v76, v0
	v_mov_b32_e32 v77, v0
	v_mov_b32_e32 v78, v0
	v_mov_b32_e32 v79, v0
	v_mov_b32_e32 v80, v0
	v_mov_b32_e32 v81, v0
	v_mov_b32_e32 v82, v0
	v_mov_b32_e32 v83, v0
	v_mov_b32_e32 v84, v0
	v_mov_b32_e32 v85, v0
	v_mov_b32_e32 v86, v0
	v_mov_b32_e32 v87, v0
	v_mov_b32_e32 v88, v0
	v_mov_b32_e32 v89, v0
	v_mov_b32_e32 v90, v0
	v_mov_b32_e32 v91, v0
	v_mov_b32_e32 v92, v0
	v_mov_b32_e32 v93, v0
	v_mov_b32_e32 v94, v0
	v_mov_b32_e32 v95, v0
	v_mov_b32_e32 v96, v0
	v_mov_b32_e32 v97, v0
	v_mov_b32_e32 v98, v0
	v_mov_b32_e32 v99, v0
	v_mov_b32_e32 v100, v0
	v_mov_b32_e32 v101, v0
	v_mov_b32_e32 v102, v0
	v_mov_b32_e32 v103, v0
	v_mov_b32_e32 v104, v0
	v_mov_b32_e32 v105, v0
	v_mov_b32_e32 v106, v0
	v_mov_b32_e32 v107, v0
	v_mov_b32_e32 v108, v0
	v_mov_b32_e32 v109, v0
	v_mov_b32_e32 v110, v0
	v_mov_b32_e32 v111, v0
	v_mov_b32_e32 v112, v0
	v_mov_b32_e32 v113, v0
	v_mov_b32_e32 v114, v0
	v_mov_b32_e32 v115, v0
	v_mov_b32_e32 v116, v0
	v_mov_b32_e32 v117, v0
	v_mov_b32_e32 v118, v0
	v_mov_b32_e32 v119, v0
	v_mov_b32_e32 v120, v0
	v_mov_b32_e32 v121, v0
	v_mov_b32_e32 v122, v0
	v_mov_b32_e32 v123, v0
	v_mov_b32_e32 v124, v0
	v_mov_b32_e32 v125, v0
	v_mov_b32_e32 v126, v0
	v_mov_b32_e32 v127, v0
	v_readfirstlane_b32 s98, v162
	s_add_i32 s21, s20, 0xfffe8000
	s_and_b32 s21, s21, 0x18000
	v_add_u32_e32 v235, s21, v160
	v_add_u32_e32 v236, s21, v161
	s_waitcnt vmcnt(8)
	s_barrier
	ds_read_b128 v[182:185], v235
	ds_read_b128 v[186:189], v235 offset:1024
	ds_read_b128 v[164:167], v236 offset:16384
	ds_read_b128 v[170:173], v236 offset:17408
	ds_read_b128 v[174:177], v236 offset:18432
	ds_read_b128 v[178:181], v236 offset:19456
	ds_read_b128 v[190:193], v235 offset:2048
	ds_read_b128 v[194:197], v235 offset:3072
	s_branch .Lmoe1_mid
; #define GEMM_WAITV(n) asm volatile("s_waitcnt vmcnt(" #n ")" ::: "memory")
; template <bool SWAP>
; __device__ __forceinline__ void gemm_main(f32x4 (&acc)[8][4], const TP& t, int nk, char* lds) {
;     ...
; #pragma unroll 1
;   for (int kt = 0; kt < nk - 3; ++kt) {
;     GEMM_WAITV(8);
;     GEMM_STEP(kt, true)
;   }
; #pragma unroll 1
;   for (int kt = nk - 3; kt < nk; ++kt) {
;     const int rem = nk - kt;
;     if (rem == 3) GEMM_WAITV(8); else if (rem == 2) GEMM_WAITV(4); else GEMM_WAITV(0);
.Lmoe1_top:
	s_add_i32 s21, s20, 0xfffe8000
	s_and_b32 s21, s21, 0x18000
	v_add_u32_e32 v235, s21, v160
	v_add_u32_e32 v236, s21, v161
	s_waitcnt vmcnt(8)
	s_barrier
	ds_read_b128 v[182:185], v235
	ds_read_b128 v[186:189], v235 offset:1024
	v_mfma_f32_16x16x32_bf16 v[28:31], v[164:167], v[190:193], v[28:31]
	v_mfma_f32_16x16x32_bf16 v[12:15], v[164:167], v[194:197], v[12:15]
	ds_read_b128 v[164:167], v236 offset:16384
	v_mfma_f32_16x16x32_bf16 v[24:27], v[170:173], v[190:193], v[24:27]
	v_mfma_f32_16x16x32_bf16 v[8:11], v[170:173], v[194:197], v[8:11]
	ds_read_b128 v[170:173], v236 offset:17408
	v_mfma_f32_16x16x32_bf16 v[20:23], v[174:177], v[190:193], v[20:23]
	v_mfma_f32_16x16x32_bf16 v[4:7], v[174:177], v[194:197], v[4:7]
	ds_read_b128 v[174:177], v236 offset:18432
	v_mfma_f32_16x16x32_bf16 v[16:19], v[178:181], v[190:193], v[16:19]
	v_mfma_f32_16x16x32_bf16 v[0:3], v[178:181], v[194:197], v[0:3]
	ds_read_b128 v[178:181], v236 offset:19456
	ds_read_b128 v[190:193], v235 offset:2048
	ds_read_b128 v[194:197], v235 offset:3072
.Lmoe1_mid:
	s_and_b32 s21, s20, 0x18000
	s_add_i32 s21, s21, s98
	s_mov_b32 m0, s21
	s_waitcnt lgkmcnt(5)
	v_mfma_f32_16x16x32_bf16 v[124:127], v[164:167], v[182:185], v[124:127]
	global_load_lds_dwordx4 v[136:137], off
	s_waitcnt lgkmcnt(4)
	v_mfma_f32_16x16x32_bf16 v[120:123], v[170:173], v[182:185], v[120:123]
	s_waitcnt lgkmcnt(3)
	v_mfma_f32_16x16x32_bf16 v[116:119], v[174:177], v[182:185], v[116:119]
	s_waitcnt lgkmcnt(2)
	v_mfma_f32_16x16x32_bf16 v[112:115], v[178:181], v[182:185], v[112:115]
	v_mfma_f32_16x16x32_bf16 v[108:111], v[164:167], v[186:189], v[108:111]
	v_mfma_f32_16x16x32_bf16 v[104:107], v[170:173], v[186:189], v[104:107]
	v_mfma_f32_16x16x32_bf16 v[100:103], v[174:177], v[186:189], v[100:103]
	v_mfma_f32_16x16x32_bf16 v[96:99], v[178:181], v[186:189], v[96:99]
	ds_read_b128 v[182:185], v235 offset:4096
	ds_read_b128 v[186:189], v235 offset:5120
	s_add_i32 m0, s21, 0x400
	s_waitcnt lgkmcnt(3)
	v_mfma_f32_16x16x32_bf16 v[92:95], v[164:167], v[190:193], v[92:95]
	global_load_lds_dwordx4 v[138:139], off
	v_mfma_f32_16x16x32_bf16 v[88:91], v[170:173], v[190:193], v[88:91]
	v_mfma_f32_16x16x32_bf16 v[84:87], v[174:177], v[190:193], v[84:87]
	v_mfma_f32_16x16x32_bf16 v[80:83], v[178:181], v[190:193], v[80:83]
	s_waitcnt lgkmcnt(2)
	v_mfma_f32_16x16x32_bf16 v[76:79], v[164:167], v[194:197], v[76:79]
	v_mfma_f32_16x16x32_bf16 v[72:75], v[170:173], v[194:197], v[72:75]
	v_mfma_f32_16x16x32_bf16 v[68:71], v[174:177], v[194:197], v[68:71]
	v_mfma_f32_16x16x32_bf16 v[64:67], v[178:181], v[194:197], v[64:67]
	ds_read_b128 v[190:193], v235 offset:6144
	ds_read_b128 v[194:197], v235 offset:7168
	s_add_i32 m0, s21, 0x4000
	s_waitcnt lgkmcnt(3)
	v_mfma_f32_16x16x32_bf16 v[60:63], v[164:167], v[182:185], v[60:63]
	global_load_lds_dwordx4 v[140:141], off
	v_mfma_f32_16x16x32_bf16 v[56:59], v[170:173], v[182:185], v[56:59]
	v_mfma_f32_16x16x32_bf16 v[52:55], v[174:177], v[182:185], v[52:55]
	v_mfma_f32_16x16x32_bf16 v[48:51], v[178:181], v[182:185], v[48:51]
	s_add_i32 m0, s21, 0x4400
	s_waitcnt lgkmcnt(2)
	v_mfma_f32_16x16x32_bf16 v[44:47], v[164:167], v[186:189], v[44:47]
	global_load_lds_dwordx4 v[142:143], off
	v_mfma_f32_16x16x32_bf16 v[40:43], v[170:173], v[186:189], v[40:43]
	v_lshl_add_u64 v[136:137], v[136:137], 0, 64
	v_lshl_add_u64 v[138:139], v[138:139], 0, 64
	v_lshl_add_u64 v[140:141], v[140:141], 0, 64
	v_lshl_add_u64 v[142:143], v[142:143], 0, 64
	s_add_i32 s20, s20, 0x8000
	v_mfma_f32_16x16x32_bf16 v[36:39], v[174:177], v[186:189], v[36:39]
	v_mfma_f32_16x16x32_bf16 v[32:35], v[178:181], v[186:189], v[32:35]
	s_waitcnt lgkmcnt(0)
	s_cmp_lg_u32 s20, 0x100000
	s_cbranch_scc1 .Lmoe1_top
	v_add_u32_e32 v235, 0x8000, v160
	v_add_u32_e32 v236, 0x8000, v161
	s_waitcnt vmcnt(8)
	s_barrier
	ds_read_b128 v[182:185], v235
	ds_read_b128 v[186:189], v235 offset:1024
	v_mfma_f32_16x16x32_bf16 v[28:31], v[164:167], v[190:193], v[28:31]
	v_mfma_f32_16x16x32_bf16 v[12:15], v[164:167], v[194:197], v[12:15]
	ds_read_b128 v[164:167], v236 offset:16384
	v_mfma_f32_16x16x32_bf16 v[24:27], v[170:173], v[190:193], v[24:27]
	v_mfma_f32_16x16x32_bf16 v[8:11], v[170:173], v[194:197], v[8:11]
	ds_read_b128 v[170:173], v236 offset:17408
	v_mfma_f32_16x16x32_bf16 v[20:23], v[174:177], v[190:193], v[20:23]
	v_mfma_f32_16x16x32_bf16 v[4:7], v[174:177], v[194:197], v[4:7]
	ds_read_b128 v[174:177], v236 offset:18432
	v_mfma_f32_16x16x32_bf16 v[16:19], v[178:181], v[190:193], v[16:19]
	v_mfma_f32_16x16x32_bf16 v[0:3], v[178:181], v[194:197], v[0:3]
	ds_read_b128 v[178:181], v236 offset:19456
	ds_read_b128 v[190:193], v235 offset:2048
	ds_read_b128 v[194:197], v235 offset:3072
	s_waitcnt lgkmcnt(5)
	v_mfma_f32_16x16x32_bf16 v[124:127], v[164:167], v[182:185], v[124:127]
	s_waitcnt lgkmcnt(4)
	v_mfma_f32_16x16x32_bf16 v[120:123], v[170:173], v[182:185], v[120:123]
	s_waitcnt lgkmcnt(3)
	v_mfma_f32_16x16x32_bf16 v[116:119], v[174:177], v[182:185], v[116:119]
	s_waitcnt lgkmcnt(2)
	v_mfma_f32_16x16x32_bf16 v[112:115], v[178:181], v[182:185], v[112:115]
	v_mfma_f32_16x16x32_bf16 v[108:111], v[164:167], v[186:189], v[108:111]
	v_mfma_f32_16x16x32_bf16 v[104:107], v[170:173], v[186:189], v[104:107]
	v_mfma_f32_16x16x32_bf16 v[100:103], v[174:177], v[186:189], v[100:103]
	v_mfma_f32_16x16x32_bf16 v[96:99], v[178:181], v[186:189], v[96:99]
	ds_read_b128 v[182:185], v235 offset:4096
	ds_read_b128 v[186:189], v235 offset:5120
	s_waitcnt lgkmcnt(3)
	v_mfma_f32_16x16x32_bf16 v[92:95], v[164:167], v[190:193], v[92:95]
	v_mfma_f32_16x16x32_bf16 v[88:91], v[170:173], v[190:193], v[88:91]
	v_mfma_f32_16x16x32_bf16 v[84:87], v[174:177], v[190:193], v[84:87]
	v_mfma_f32_16x16x32_bf16 v[80:83], v[178:181], v[190:193], v[80:83]
	s_waitcnt lgkmcnt(2)
	v_mfma_f32_16x16x32_bf16 v[76:79], v[164:167], v[194:197], v[76:79]
	v_mfma_f32_16x16x32_bf16 v[72:75], v[170:173], v[194:197], v[72:75]
	v_mfma_f32_16x16x32_bf16 v[68:71], v[174:177], v[194:197], v[68:71]
	v_mfma_f32_16x16x32_bf16 v[64:67], v[178:181], v[194:197], v[64:67]
	ds_read_b128 v[190:193], v235 offset:6144
	ds_read_b128 v[194:197], v235 offset:7168
	s_waitcnt lgkmcnt(3)
	v_mfma_f32_16x16x32_bf16 v[60:63], v[164:167], v[182:185], v[60:63]
	v_mfma_f32_16x16x32_bf16 v[56:59], v[170:173], v[182:185], v[56:59]
	v_mfma_f32_16x16x32_bf16 v[52:55], v[174:177], v[182:185], v[52:55]
	v_mfma_f32_16x16x32_bf16 v[48:51], v[178:181], v[182:185], v[48:51]
	s_waitcnt lgkmcnt(2)
	v_mfma_f32_16x16x32_bf16 v[44:47], v[164:167], v[186:189], v[44:47]
	v_mfma_f32_16x16x32_bf16 v[40:43], v[170:173], v[186:189], v[40:43]
	v_mfma_f32_16x16x32_bf16 v[36:39], v[174:177], v[186:189], v[36:39]
	v_mfma_f32_16x16x32_bf16 v[32:35], v[178:181], v[186:189], v[32:35]
	s_waitcnt lgkmcnt(0)
	v_add_u32_e32 v235, 0x10000, v160
	v_add_u32_e32 v236, 0x10000, v161
	s_waitcnt vmcnt(4)
	s_barrier
; #define GEMM_WAITV(n) asm volatile("s_waitcnt vmcnt(" #n ")" ::: "memory")
; template <bool SWAP>
; __device__ __forceinline__ void gemm_main(f32x4 (&acc)[8][4], const TP& t, int nk, char* lds) {
;     ...
; #pragma unroll 1
;   for (int kt = 0; kt < nk - 3; ++kt) {
;     GEMM_WAITV(8);
;     GEMM_STEP(kt, true)
;   }
; #pragma unroll 1
;   for (int kt = nk - 3; kt < nk; ++kt) {
;     const int rem = nk - kt;
;     if (rem == 3) GEMM_WAITV(8); else if (rem == 2) GEMM_WAITV(4); else GEMM_WAITV(0);
;     GEMM_STEP(kt, false)
;   }
;   __builtin_amdgcn_s_barrier();
	ds_read_b128 v[182:185], v235
	ds_read_b128 v[186:189], v235 offset:1024
	v_mfma_f32_16x16x32_bf16 v[28:31], v[164:167], v[190:193], v[28:31]
	v_mfma_f32_16x16x32_bf16 v[12:15], v[164:167], v[194:197], v[12:15]
	ds_read_b128 v[164:167], v236 offset:16384
	v_mfma_f32_16x16x32_bf16 v[24:27], v[170:173], v[190:193], v[24:27]
	v_mfma_f32_16x16x32_bf16 v[8:11], v[170:173], v[194:197], v[8:11]
	ds_read_b128 v[170:173], v236 offset:17408
	v_mfma_f32_16x16x32_bf16 v[20:23], v[174:177], v[190:193], v[20:23]
	v_mfma_f32_16x16x32_bf16 v[4:7], v[174:177], v[194:197], v[4:7]
	ds_read_b128 v[174:177], v236 offset:18432
	v_mfma_f32_16x16x32_bf16 v[16:19], v[178:181], v[190:193], v[16:19]
	v_mfma_f32_16x16x32_bf16 v[0:3], v[178:181], v[194:197], v[0:3]
	ds_read_b128 v[178:181], v236 offset:19456
	ds_read_b128 v[190:193], v235 offset:2048
	ds_read_b128 v[194:197], v235 offset:3072
	s_waitcnt lgkmcnt(5)
	v_mfma_f32_16x16x32_bf16 v[124:127], v[164:167], v[182:185], v[124:127]
	s_waitcnt lgkmcnt(4)
	v_mfma_f32_16x16x32_bf16 v[120:123], v[170:173], v[182:185], v[120:123]
	s_waitcnt lgkmcnt(3)
	v_mfma_f32_16x16x32_bf16 v[116:119], v[174:177], v[182:185], v[116:119]
	s_waitcnt lgkmcnt(2)
	v_mfma_f32_16x16x32_bf16 v[112:115], v[178:181], v[182:185], v[112:115]
	v_mfma_f32_16x16x32_bf16 v[108:111], v[164:167], v[186:189], v[108:111]
	v_mfma_f32_16x16x32_bf16 v[104:107], v[170:173], v[186:189], v[104:107]
	v_mfma_f32_16x16x32_bf16 v[100:103], v[174:177], v[186:189], v[100:103]
	v_mfma_f32_16x16x32_bf16 v[96:99], v[178:181], v[186:189], v[96:99]
	ds_read_b128 v[182:185], v235 offset:4096
	ds_read_b128 v[186:189], v235 offset:5120
	s_waitcnt lgkmcnt(3)
	v_mfma_f32_16x16x32_bf16 v[92:95], v[164:167], v[190:193], v[92:95]
	v_mfma_f32_16x16x32_bf16 v[88:91], v[170:173], v[190:193], v[88:91]
	v_mfma_f32_16x16x32_bf16 v[84:87], v[174:177], v[190:193], v[84:87]
	v_mfma_f32_16x16x32_bf16 v[80:83], v[178:181], v[190:193], v[80:83]
	s_waitcnt lgkmcnt(2)
	v_mfma_f32_16x16x32_bf16 v[76:79], v[164:167], v[194:197], v[76:79]
	v_mfma_f32_16x16x32_bf16 v[72:75], v[170:173], v[194:197], v[72:75]
	v_mfma_f32_16x16x32_bf16 v[68:71], v[174:177], v[194:197], v[68:71]
	v_mfma_f32_16x16x32_bf16 v[64:67], v[178:181], v[194:197], v[64:67]
	ds_read_b128 v[190:193], v235 offset:6144
	ds_read_b128 v[194:197], v235 offset:7168
	s_waitcnt lgkmcnt(3)
	v_mfma_f32_16x16x32_bf16 v[60:63], v[164:167], v[182:185], v[60:63]
	v_mfma_f32_16x16x32_bf16 v[56:59], v[170:173], v[182:185], v[56:59]
	v_mfma_f32_16x16x32_bf16 v[52:55], v[174:177], v[182:185], v[52:55]
	v_mfma_f32_16x16x32_bf16 v[48:51], v[178:181], v[182:185], v[48:51]
	s_waitcnt lgkmcnt(2)
	v_mfma_f32_16x16x32_bf16 v[44:47], v[164:167], v[186:189], v[44:47]
	v_mfma_f32_16x16x32_bf16 v[40:43], v[170:173], v[186:189], v[40:43]
	v_mfma_f32_16x16x32_bf16 v[36:39], v[174:177], v[186:189], v[36:39]
	v_mfma_f32_16x16x32_bf16 v[32:35], v[178:181], v[186:189], v[32:35]
	s_waitcnt lgkmcnt(0)
	v_add_u32_e32 v235, 0x18000, v160
	v_add_u32_e32 v236, 0x18000, v161
	s_waitcnt vmcnt(0)
	s_barrier
	ds_read_b128 v[182:185], v235
	ds_read_b128 v[186:189], v235 offset:1024
	v_mfma_f32_16x16x32_bf16 v[28:31], v[164:167], v[190:193], v[28:31]
	v_mfma_f32_16x16x32_bf16 v[12:15], v[164:167], v[194:197], v[12:15]
	ds_read_b128 v[164:167], v236 offset:16384
	v_mfma_f32_16x16x32_bf16 v[24:27], v[170:173], v[190:193], v[24:27]
	v_mfma_f32_16x16x32_bf16 v[8:11], v[170:173], v[194:197], v[8:11]
	ds_read_b128 v[170:173], v236 offset:17408
	v_mfma_f32_16x16x32_bf16 v[20:23], v[174:177], v[190:193], v[20:23]
	v_mfma_f32_16x16x32_bf16 v[4:7], v[174:177], v[194:197], v[4:7]
	ds_read_b128 v[174:177], v236 offset:18432
	v_mfma_f32_16x16x32_bf16 v[16:19], v[178:181], v[190:193], v[16:19]
	v_mfma_f32_16x16x32_bf16 v[0:3], v[178:181], v[194:197], v[0:3]
	ds_read_b128 v[178:181], v236 offset:19456
	ds_read_b128 v[190:193], v235 offset:2048
	ds_read_b128 v[194:197], v235 offset:3072
	s_waitcnt lgkmcnt(5)
	v_mfma_f32_16x16x32_bf16 v[124:127], v[164:167], v[182:185], v[124:127]
	s_waitcnt lgkmcnt(4)
	v_mfma_f32_16x16x32_bf16 v[120:123], v[170:173], v[182:185], v[120:123]
	s_waitcnt lgkmcnt(3)
	v_mfma_f32_16x16x32_bf16 v[116:119], v[174:177], v[182:185], v[116:119]
	s_waitcnt lgkmcnt(2)
	v_mfma_f32_16x16x32_bf16 v[112:115], v[178:181], v[182:185], v[112:115]
	v_mfma_f32_16x16x32_bf16 v[108:111], v[164:167], v[186:189], v[108:111]
	v_mfma_f32_16x16x32_bf16 v[104:107], v[170:173], v[186:189], v[104:107]
	v_mfma_f32_16x16x32_bf16 v[100:103], v[174:177], v[186:189], v[100:103]
	v_mfma_f32_16x16x32_bf16 v[96:99], v[178:181], v[186:189], v[96:99]
	ds_read_b128 v[182:185], v235 offset:4096
	ds_read_b128 v[186:189], v235 offset:5120
	s_waitcnt lgkmcnt(3)
	v_mfma_f32_16x16x32_bf16 v[92:95], v[164:167], v[190:193], v[92:95]
	v_mfma_f32_16x16x32_bf16 v[88:91], v[170:173], v[190:193], v[88:91]
	v_mfma_f32_16x16x32_bf16 v[84:87], v[174:177], v[190:193], v[84:87]
	v_mfma_f32_16x16x32_bf16 v[80:83], v[178:181], v[190:193], v[80:83]
	s_waitcnt lgkmcnt(2)
	v_mfma_f32_16x16x32_bf16 v[76:79], v[164:167], v[194:197], v[76:79]
	v_mfma_f32_16x16x32_bf16 v[72:75], v[170:173], v[194:197], v[72:75]
	v_mfma_f32_16x16x32_bf16 v[68:71], v[174:177], v[194:197], v[68:71]
	v_mfma_f32_16x16x32_bf16 v[64:67], v[178:181], v[194:197], v[64:67]
	ds_read_b128 v[190:193], v235 offset:6144
	ds_read_b128 v[194:197], v235 offset:7168
	s_waitcnt lgkmcnt(3)
	v_mfma_f32_16x16x32_bf16 v[60:63], v[164:167], v[182:185], v[60:63]
	v_mfma_f32_16x16x32_bf16 v[56:59], v[170:173], v[182:185], v[56:59]
	v_mfma_f32_16x16x32_bf16 v[52:55], v[174:177], v[182:185], v[52:55]
	v_mfma_f32_16x16x32_bf16 v[48:51], v[178:181], v[182:185], v[48:51]
	s_waitcnt lgkmcnt(2)
	v_mfma_f32_16x16x32_bf16 v[44:47], v[164:167], v[186:189], v[44:47]
	v_mfma_f32_16x16x32_bf16 v[40:43], v[170:173], v[186:189], v[40:43]
	v_mfma_f32_16x16x32_bf16 v[36:39], v[174:177], v[186:189], v[36:39]
	v_mfma_f32_16x16x32_bf16 v[32:35], v[178:181], v[186:189], v[32:35]
	s_waitcnt lgkmcnt(0)
	v_mfma_f32_16x16x32_bf16 v[28:31], v[164:167], v[190:193], v[28:31]
	v_mfma_f32_16x16x32_bf16 v[12:15], v[164:167], v[194:197], v[12:15]
	v_mfma_f32_16x16x32_bf16 v[24:27], v[170:173], v[190:193], v[24:27]
	v_mfma_f32_16x16x32_bf16 v[8:11], v[170:173], v[194:197], v[8:11]
	v_mfma_f32_16x16x32_bf16 v[20:23], v[174:177], v[190:193], v[20:23]
	v_mfma_f32_16x16x32_bf16 v[4:7], v[174:177], v[194:197], v[4:7]
	v_mfma_f32_16x16x32_bf16 v[16:19], v[178:181], v[190:193], v[16:19]
	v_mfma_f32_16x16x32_bf16 v[0:3], v[178:181], v[194:197], v[0:3]
	s_nop 7

; __device__ __forceinline__ void zero_acc(f32x4 (&acc)[8][4]) {
; #pragma unroll
;   for (int i = 0; i < 8; ++i)
; #pragma unroll
;     for (int j = 0; j < 4; ++j) acc[i][j] = (f32x4){0.f, 0.f, 0.f, 0.f};
.LBB0_1368:
	v_mov_b32_e32 v146, v153
	v_mov_b32_e32 v134, v153
	v_mov_b32_e32 v145, v153
	v_mov_b32_e32 v142, v153
	v_mov_b32_e32 v144, v153
	v_mov_b32_e32 v143, v153
	v_mov_b32_e32 v0, v153
	s_mov_b64 s[14:15], 0x160c0
	v_lshlrev_b32_e32 v3, 2, v0
	v_and_b32_e32 v3, 48, v3
	v_sub_u32_e32 v3, 0, v3
	v_and_b32_e32 v147, 15, v0
	v_lshlrev_b32_e32 v1, 5, v0
	v_lshlrev_b32_e32 v2, 4, v0
	v_bitop3_b32 v149, v0, 48, v3 bitop3:0x48
	v_ashrrev_i32_e32 v151, 1, v0
	v_lshlrev_b32_e32 v0, 6, v0
	v_and_b32_e32 v1, 0xfffff800, v1
	v_and_b32_e32 v2, 0x3f0, v2
	v_and_or_b32 v3, v151, s2, v147
	v_and_b32_e32 v154, 0x33c0, v0
	v_mov_b32_e32 v0, 0
	s_mov_b32 s22, s18
	v_lshl_or_b32 v155, v3, 6, v149
	v_or_b32_e32 v156, v154, v149
	v_add3_u32 v157, 0, v1, v2
	v_lshl_add_u64 v[136:137], v[136:137], 0, s[14:15]
	v_lshl_add_u64 v[138:139], v[138:139], 0, s[42:43]
	v_lshl_add_u64 v[140:141], v[140:141], 0, s[42:43]
	s_mov_b32 s14, 0x18000
	v_mov_b32_e32 v1, v0
	v_mov_b32_e32 v2, v0
	v_mov_b32_e32 v3, v0
	v_mov_b32_e32 v4, v0
	v_mov_b32_e32 v5, v0
	v_mov_b32_e32 v6, v0
	v_mov_b32_e32 v7, v0
	v_mov_b32_e32 v8, v0
	v_mov_b32_e32 v9, v0
	v_mov_b32_e32 v10, v0
	v_mov_b32_e32 v11, v0
	v_mov_b32_e32 v12, v0
	v_mov_b32_e32 v13, v0
	v_mov_b32_e32 v14, v0
	v_mov_b32_e32 v15, v0
	v_mov_b32_e32 v16, v0
	v_mov_b32_e32 v17, v0
	v_mov_b32_e32 v18, v0
	v_mov_b32_e32 v19, v0
	v_mov_b32_e32 v20, v0
	v_mov_b32_e32 v21, v0
	v_mov_b32_e32 v22, v0
	v_mov_b32_e32 v23, v0
	v_mov_b32_e32 v24, v0
	v_mov_b32_e32 v25, v0
	v_mov_b32_e32 v26, v0
	v_mov_b32_e32 v27, v0
	v_mov_b32_e32 v28, v0
	v_mov_b32_e32 v29, v0
	v_mov_b32_e32 v30, v0
	v_mov_b32_e32 v31, v0
	v_mov_b32_e32 v32, v0
	v_mov_b32_e32 v33, v0
	v_mov_b32_e32 v34, v0
	v_mov_b32_e32 v35, v0
	v_mov_b32_e32 v36, v0
	v_mov_b32_e32 v37, v0
	v_mov_b32_e32 v38, v0
	v_mov_b32_e32 v39, v0
	v_mov_b32_e32 v40, v0
	v_mov_b32_e32 v41, v0
	v_mov_b32_e32 v42, v0
	v_mov_b32_e32 v43, v0
	v_mov_b32_e32 v44, v0
	v_mov_b32_e32 v45, v0
	v_mov_b32_e32 v46, v0
	v_mov_b32_e32 v47, v0
	v_mov_b32_e32 v48, v0
	v_mov_b32_e32 v49, v0
	v_mov_b32_e32 v50, v0
	v_mov_b32_e32 v51, v0
	v_mov_b32_e32 v52, v0
	v_mov_b32_e32 v53, v0
	v_mov_b32_e32 v54, v0
	v_mov_b32_e32 v55, v0
	v_mov_b32_e32 v56, v0
	v_mov_b32_e32 v57, v0
	v_mov_b32_e32 v58, v0
	v_mov_b32_e32 v59, v0
	v_mov_b32_e32 v60, v0
	v_mov_b32_e32 v61, v0
	v_mov_b32_e32 v62, v0
	v_mov_b32_e32 v63, v0
	v_mov_b32_e32 v64, v0
	v_mov_b32_e32 v65, v0
	v_mov_b32_e32 v66, v0
	v_mov_b32_e32 v67, v0
	v_mov_b32_e32 v68, v0
	v_mov_b32_e32 v69, v0
	v_mov_b32_e32 v70, v0
	v_mov_b32_e32 v71, v0
	v_mov_b32_e32 v72, v0
	v_mov_b32_e32 v73, v0
	v_mov_b32_e32 v74, v0
	v_mov_b32_e32 v75, v0
	v_mov_b32_e32 v76, v0
	v_mov_b32_e32 v77, v0
	v_mov_b32_e32 v78, v0
	v_mov_b32_e32 v79, v0
	v_mov_b32_e32 v80, v0
	v_mov_b32_e32 v81, v0
	v_mov_b32_e32 v82, v0
	v_mov_b32_e32 v83, v0
	v_mov_b32_e32 v84, v0
	v_mov_b32_e32 v85, v0
	v_mov_b32_e32 v86, v0
	v_mov_b32_e32 v87, v0
	v_mov_b32_e32 v88, v0
	v_mov_b32_e32 v89, v0
	v_mov_b32_e32 v90, v0
	v_mov_b32_e32 v91, v0
	v_mov_b32_e32 v92, v0
	v_mov_b32_e32 v93, v0
	v_mov_b32_e32 v94, v0
	v_mov_b32_e32 v95, v0
	v_mov_b32_e32 v96, v0
	v_mov_b32_e32 v97, v0
	v_mov_b32_e32 v98, v0
	v_mov_b32_e32 v99, v0
	v_mov_b32_e32 v100, v0
	v_mov_b32_e32 v101, v0
	v_mov_b32_e32 v102, v0
	v_mov_b32_e32 v103, v0
	v_mov_b32_e32 v104, v0
	v_mov_b32_e32 v105, v0
	v_mov_b32_e32 v106, v0
	v_mov_b32_e32 v107, v0
	v_mov_b32_e32 v108, v0
	v_mov_b32_e32 v109, v0
	v_mov_b32_e32 v110, v0
	v_mov_b32_e32 v111, v0
	v_mov_b32_e32 v112, v0
	v_mov_b32_e32 v113, v0
	v_mov_b32_e32 v114, v0
	v_mov_b32_e32 v115, v0
	v_mov_b32_e32 v116, v0
	v_mov_b32_e32 v117, v0
	v_mov_b32_e32 v118, v0
	v_mov_b32_e32 v119, v0
	v_mov_b32_e32 v120, v0
	v_mov_b32_e32 v121, v0
	v_mov_b32_e32 v122, v0
	v_mov_b32_e32 v123, v0
	v_mov_b32_e32 v124, v0
	v_mov_b32_e32 v125, v0
	v_mov_b32_e32 v126, v0
	v_mov_b32_e32 v127, v0
	s_mov_b32 s18, 0xfffea000
	s_mov_b32 s19, -1
	v_readfirstlane_b32 s98, v157
	s_add_i32 s15, s14, 0xfffe8000
	s_and_b32 s15, s15, 0x18000
	v_add_u32_e32 v235, s15, v155
	v_add_u32_e32 v236, s15, v156
	s_waitcnt vmcnt(8)
	s_barrier
	ds_read_b128 v[178:181], v235
	ds_read_b128 v[182:185], v235 offset:1024
	ds_read_b128 v[158:161], v236 offset:16384
	ds_read_b128 v[162:165], v236 offset:17408
	ds_read_b128 v[170:173], v236 offset:18432
	ds_read_b128 v[174:177], v236 offset:19456
	ds_read_b128 v[186:189], v235 offset:2048
	ds_read_b128 v[190:193], v235 offset:3072
	s_branch .Lmoe2_mid
.Lmoe2_top:
	s_add_i32 s15, s14, 0xfffe8000
	s_and_b32 s15, s15, 0x18000
	v_add_u32_e32 v235, s15, v155
	v_add_u32_e32 v236, s15, v156
	s_waitcnt vmcnt(8)
	s_barrier
	ds_read_b128 v[178:181], v235
	ds_read_b128 v[182:185], v235 offset:1024
	v_mfma_f32_16x16x32_bf16 v[28:31], v[158:161], v[186:189], v[28:31]
	v_mfma_f32_16x16x32_bf16 v[12:15], v[158:161], v[190:193], v[12:15]
	ds_read_b128 v[158:161], v236 offset:16384
	v_mfma_f32_16x16x32_bf16 v[24:27], v[162:165], v[186:189], v[24:27]
	v_mfma_f32_16x16x32_bf16 v[8:11], v[162:165], v[190:193], v[8:11]
	ds_read_b128 v[162:165], v236 offset:17408
	v_mfma_f32_16x16x32_bf16 v[20:23], v[170:173], v[186:189], v[20:23]
	v_mfma_f32_16x16x32_bf16 v[4:7], v[170:173], v[190:193], v[4:7]
	ds_read_b128 v[170:173], v236 offset:18432
	v_mfma_f32_16x16x32_bf16 v[16:19], v[174:177], v[186:189], v[16:19]
	v_mfma_f32_16x16x32_bf16 v[0:3], v[174:177], v[190:193], v[0:3]
	ds_read_b128 v[174:177], v236 offset:19456
	ds_read_b128 v[186:189], v235 offset:2048
	ds_read_b128 v[190:193], v235 offset:3072
; #define GEMM_WAITV(n) asm volatile("s_waitcnt vmcnt(" #n ")" ::: "memory")
; template <bool SWAP>
; __device__ __forceinline__ void gemm_main(f32x4 (&acc)[8][4], const TP& t, int nk, char* lds) {
;     ...
; #pragma unroll 1
;   for (int kt = 0; kt < nk - 3; ++kt) {
;     GEMM_WAITV(8);
;     GEMM_STEP(kt, true)
;   }
; #pragma unroll 1
;   for (int kt = nk - 3; kt < nk; ++kt) {
;     const int rem = nk - kt;
;     if (rem == 3) GEMM_WAITV(8); else if (rem == 2) GEMM_WAITV(4); else GEMM_WAITV(0);
.Lmoe2_mid:
	s_and_b32 s15, s14, 0x18000
	s_add_i32 s15, s15, s98
	s_mov_b32 m0, s15
	v_lshl_add_u64 v[238:239], v[136:137], 0, s[18:19]
	s_waitcnt lgkmcnt(5)
	v_mfma_f32_16x16x32_bf16 v[124:127], v[158:161], v[178:181], v[124:127]
	global_load_lds_dwordx4 v[238:239], off
	s_waitcnt lgkmcnt(4)
	v_mfma_f32_16x16x32_bf16 v[120:123], v[162:165], v[178:181], v[120:123]
	s_waitcnt lgkmcnt(3)
	v_mfma_f32_16x16x32_bf16 v[116:119], v[170:173], v[178:181], v[116:119]
	s_waitcnt lgkmcnt(2)
	v_mfma_f32_16x16x32_bf16 v[112:115], v[174:177], v[178:181], v[112:115]
	v_mfma_f32_16x16x32_bf16 v[108:111], v[158:161], v[182:185], v[108:111]
	v_mfma_f32_16x16x32_bf16 v[104:107], v[162:165], v[182:185], v[104:107]
	v_mfma_f32_16x16x32_bf16 v[100:103], v[170:173], v[182:185], v[100:103]
	v_mfma_f32_16x16x32_bf16 v[96:99], v[174:177], v[182:185], v[96:99]
	ds_read_b128 v[178:181], v235 offset:4096
	ds_read_b128 v[182:185], v235 offset:5120
	s_add_i32 m0, s15, 0x400
	s_waitcnt lgkmcnt(3)
	v_mfma_f32_16x16x32_bf16 v[92:95], v[158:161], v[186:189], v[92:95]
	global_load_lds_dwordx4 v[136:137], off
	v_mfma_f32_16x16x32_bf16 v[88:91], v[162:165], v[186:189], v[88:91]
	v_mfma_f32_16x16x32_bf16 v[84:87], v[170:173], v[186:189], v[84:87]
	v_mfma_f32_16x16x32_bf16 v[80:83], v[174:177], v[186:189], v[80:83]
	s_waitcnt lgkmcnt(2)
	v_mfma_f32_16x16x32_bf16 v[76:79], v[158:161], v[190:193], v[76:79]
	v_mfma_f32_16x16x32_bf16 v[72:75], v[162:165], v[190:193], v[72:75]
	v_mfma_f32_16x16x32_bf16 v[68:71], v[170:173], v[190:193], v[68:71]
	v_mfma_f32_16x16x32_bf16 v[64:67], v[174:177], v[190:193], v[64:67]
	ds_read_b128 v[186:189], v235 offset:6144
	ds_read_b128 v[190:193], v235 offset:7168
	s_add_i32 m0, s15, 0x4000
	s_waitcnt lgkmcnt(3)
	v_mfma_f32_16x16x32_bf16 v[60:63], v[158:161], v[178:181], v[60:63]
	global_load_lds_dwordx4 v[138:139], off
	v_mfma_f32_16x16x32_bf16 v[56:59], v[162:165], v[178:181], v[56:59]
	v_mfma_f32_16x16x32_bf16 v[52:55], v[170:173], v[178:181], v[52:55]
	v_mfma_f32_16x16x32_bf16 v[48:51], v[174:177], v[178:181], v[48:51]
	s_add_i32 m0, s15, 0x4400
	s_waitcnt lgkmcnt(2)
	v_mfma_f32_16x16x32_bf16 v[44:47], v[158:161], v[182:185], v[44:47]
	global_load_lds_dwordx4 v[140:141], off
	v_mfma_f32_16x16x32_bf16 v[40:43], v[162:165], v[182:185], v[40:43]
	v_lshl_add_u64 v[136:137], v[136:137], 0, 64
	v_lshl_add_u64 v[138:139], v[138:139], 0, 64
	v_lshl_add_u64 v[140:141], v[140:141], 0, 64
	s_add_i32 s14, s14, 0x8000
	v_mfma_f32_16x16x32_bf16 v[36:39], v[170:173], v[182:185], v[36:39]
	v_mfma_f32_16x16x32_bf16 v[32:35], v[174:177], v[182:185], v[32:35]
	s_waitcnt lgkmcnt(0)
	s_cmp_lg_u32 s14, 0x2c0000
	s_cbranch_scc1 .Lmoe2_top
	v_add_u32_e32 v235, 0x8000, v155
	v_add_u32_e32 v236, 0x8000, v156
	s_waitcnt vmcnt(8)
	s_barrier
	ds_read_b128 v[178:181], v235
	ds_read_b128 v[182:185], v235 offset:1024
	v_mfma_f32_16x16x32_bf16 v[28:31], v[158:161], v[186:189], v[28:31]
	v_mfma_f32_16x16x32_bf16 v[12:15], v[158:161], v[190:193], v[12:15]
	ds_read_b128 v[158:161], v236 offset:16384
	v_mfma_f32_16x16x32_bf16 v[24:27], v[162:165], v[186:189], v[24:27]
	v_mfma_f32_16x16x32_bf16 v[8:11], v[162:165], v[190:193], v[8:11]
	ds_read_b128 v[162:165], v236 offset:17408
	v_mfma_f32_16x16x32_bf16 v[20:23], v[170:173], v[186:189], v[20:23]
	v_mfma_f32_16x16x32_bf16 v[4:7], v[170:173], v[190:193], v[4:7]
	ds_read_b128 v[170:173], v236 offset:18432
	v_mfma_f32_16x16x32_bf16 v[16:19], v[174:177], v[186:189], v[16:19]
	v_mfma_f32_16x16x32_bf16 v[0:3], v[174:177], v[190:193], v[0:3]
	ds_read_b128 v[174:177], v236 offset:19456
	ds_read_b128 v[186:189], v235 offset:2048
	ds_read_b128 v[190:193], v235 offset:3072
	s_waitcnt lgkmcnt(5)
	v_mfma_f32_16x16x32_bf16 v[124:127], v[158:161], v[178:181], v[124:127]
	s_waitcnt lgkmcnt(4)
	v_mfma_f32_16x16x32_bf16 v[120:123], v[162:165], v[178:181], v[120:123]
	s_waitcnt lgkmcnt(3)
	v_mfma_f32_16x16x32_bf16 v[116:119], v[170:173], v[178:181], v[116:119]
	s_waitcnt lgkmcnt(2)
	v_mfma_f32_16x16x32_bf16 v[112:115], v[174:177], v[178:181], v[112:115]
	v_mfma_f32_16x16x32_bf16 v[108:111], v[158:161], v[182:185], v[108:111]
	v_mfma_f32_16x16x32_bf16 v[104:107], v[162:165], v[182:185], v[104:107]
	v_mfma_f32_16x16x32_bf16 v[100:103], v[170:173], v[182:185], v[100:103]
	v_mfma_f32_16x16x32_bf16 v[96:99], v[174:177], v[182:185], v[96:99]
	ds_read_b128 v[178:181], v235 offset:4096
	ds_read_b128 v[182:185], v235 offset:5120
	s_waitcnt lgkmcnt(3)
	v_mfma_f32_16x16x32_bf16 v[92:95], v[158:161], v[186:189], v[92:95]
	v_mfma_f32_16x16x32_bf16 v[88:91], v[162:165], v[186:189], v[88:91]
	v_mfma_f32_16x16x32_bf16 v[84:87], v[170:173], v[186:189], v[84:87]
	v_mfma_f32_16x16x32_bf16 v[80:83], v[174:177], v[186:189], v[80:83]
	s_waitcnt lgkmcnt(2)
	v_mfma_f32_16x16x32_bf16 v[76:79], v[158:161], v[190:193], v[76:79]
	v_mfma_f32_16x16x32_bf16 v[72:75], v[162:165], v[190:193], v[72:75]
	v_mfma_f32_16x16x32_bf16 v[68:71], v[170:173], v[190:193], v[68:71]
	v_mfma_f32_16x16x32_bf16 v[64:67], v[174:177], v[190:193], v[64:67]
	ds_read_b128 v[186:189], v235 offset:6144
	ds_read_b128 v[190:193], v235 offset:7168
	s_waitcnt lgkmcnt(3)
	v_mfma_f32_16x16x32_bf16 v[60:63], v[158:161], v[178:181], v[60:63]
	v_mfma_f32_16x16x32_bf16 v[56:59], v[162:165], v[178:181], v[56:59]
	v_mfma_f32_16x16x32_bf16 v[52:55], v[170:173], v[178:181], v[52:55]
	v_mfma_f32_16x16x32_bf16 v[48:51], v[174:177], v[178:181], v[48:51]
	s_waitcnt lgkmcnt(2)
	v_mfma_f32_16x16x32_bf16 v[44:47], v[158:161], v[182:185], v[44:47]
	v_mfma_f32_16x16x32_bf16 v[40:43], v[162:165], v[182:185], v[40:43]
	v_mfma_f32_16x16x32_bf16 v[36:39], v[170:173], v[182:185], v[36:39]
	v_mfma_f32_16x16x32_bf16 v[32:35], v[174:177], v[182:185], v[32:35]
	s_waitcnt lgkmcnt(0)
	v_add_u32_e32 v235, 0x10000, v155
	v_add_u32_e32 v236, 0x10000, v156
	s_waitcnt vmcnt(4)
	s_barrier
; #define GEMM_WAITV(n) asm volatile("s_waitcnt vmcnt(" #n ")" ::: "memory")
; template <bool SWAP>
; __device__ __forceinline__ void gemm_main(f32x4 (&acc)[8][4], const TP& t, int nk, char* lds) {
;     ...
; #pragma unroll 1
;   for (int kt = 0; kt < nk - 3; ++kt) {
;     GEMM_WAITV(8);
;     GEMM_STEP(kt, true)
;   }
; #pragma unroll 1
;   for (int kt = nk - 3; kt < nk; ++kt) {
;     const int rem = nk - kt;
;     if (rem == 3) GEMM_WAITV(8); else if (rem == 2) GEMM_WAITV(4); else GEMM_WAITV(0);
;     GEMM_STEP(kt, false)
;   }
;   __builtin_amdgcn_s_barrier();
	ds_read_b128 v[178:181], v235
	ds_read_b128 v[182:185], v235 offset:1024
	v_mfma_f32_16x16x32_bf16 v[28:31], v[158:161], v[186:189], v[28:31]
	v_mfma_f32_16x16x32_bf16 v[12:15], v[158:161], v[190:193], v[12:15]
	ds_read_b128 v[158:161], v236 offset:16384
	v_mfma_f32_16x16x32_bf16 v[24:27], v[162:165], v[186:189], v[24:27]
	v_mfma_f32_16x16x32_bf16 v[8:11], v[162:165], v[190:193], v[8:11]
	ds_read_b128 v[162:165], v236 offset:17408
	v_mfma_f32_16x16x32_bf16 v[20:23], v[170:173], v[186:189], v[20:23]
	v_mfma_f32_16x16x32_bf16 v[4:7], v[170:173], v[190:193], v[4:7]
	ds_read_b128 v[170:173], v236 offset:18432
	v_mfma_f32_16x16x32_bf16 v[16:19], v[174:177], v[186:189], v[16:19]
	v_mfma_f32_16x16x32_bf16 v[0:3], v[174:177], v[190:193], v[0:3]
	ds_read_b128 v[174:177], v236 offset:19456
	ds_read_b128 v[186:189], v235 offset:2048
	ds_read_b128 v[190:193], v235 offset:3072
	s_waitcnt lgkmcnt(5)
	v_mfma_f32_16x16x32_bf16 v[124:127], v[158:161], v[178:181], v[124:127]
	s_waitcnt lgkmcnt(4)
	v_mfma_f32_16x16x32_bf16 v[120:123], v[162:165], v[178:181], v[120:123]
	s_waitcnt lgkmcnt(3)
	v_mfma_f32_16x16x32_bf16 v[116:119], v[170:173], v[178:181], v[116:119]
	s_waitcnt lgkmcnt(2)
	v_mfma_f32_16x16x32_bf16 v[112:115], v[174:177], v[178:181], v[112:115]
	v_mfma_f32_16x16x32_bf16 v[108:111], v[158:161], v[182:185], v[108:111]
	v_mfma_f32_16x16x32_bf16 v[104:107], v[162:165], v[182:185], v[104:107]
	v_mfma_f32_16x16x32_bf16 v[100:103], v[170:173], v[182:185], v[100:103]
	v_mfma_f32_16x16x32_bf16 v[96:99], v[174:177], v[182:185], v[96:99]
	ds_read_b128 v[178:181], v235 offset:4096
	ds_read_b128 v[182:185], v235 offset:5120
	s_waitcnt lgkmcnt(3)
	v_mfma_f32_16x16x32_bf16 v[92:95], v[158:161], v[186:189], v[92:95]
	v_mfma_f32_16x16x32_bf16 v[88:91], v[162:165], v[186:189], v[88:91]
	v_mfma_f32_16x16x32_bf16 v[84:87], v[170:173], v[186:189], v[84:87]
	v_mfma_f32_16x16x32_bf16 v[80:83], v[174:177], v[186:189], v[80:83]
	s_waitcnt lgkmcnt(2)
	v_mfma_f32_16x16x32_bf16 v[76:79], v[158:161], v[190:193], v[76:79]
	v_mfma_f32_16x16x32_bf16 v[72:75], v[162:165], v[190:193], v[72:75]
	v_mfma_f32_16x16x32_bf16 v[68:71], v[170:173], v[190:193], v[68:71]
	v_mfma_f32_16x16x32_bf16 v[64:67], v[174:177], v[190:193], v[64:67]
	ds_read_b128 v[186:189], v235 offset:6144
	ds_read_b128 v[190:193], v235 offset:7168
	s_waitcnt lgkmcnt(3)
	v_mfma_f32_16x16x32_bf16 v[60:63], v[158:161], v[178:181], v[60:63]
	v_mfma_f32_16x16x32_bf16 v[56:59], v[162:165], v[178:181], v[56:59]
	v_mfma_f32_16x16x32_bf16 v[52:55], v[170:173], v[178:181], v[52:55]
	v_mfma_f32_16x16x32_bf16 v[48:51], v[174:177], v[178:181], v[48:51]
	s_waitcnt lgkmcnt(2)
	v_mfma_f32_16x16x32_bf16 v[44:47], v[158:161], v[182:185], v[44:47]
	v_mfma_f32_16x16x32_bf16 v[40:43], v[162:165], v[182:185], v[40:43]
	v_mfma_f32_16x16x32_bf16 v[36:39], v[170:173], v[182:185], v[36:39]
	v_mfma_f32_16x16x32_bf16 v[32:35], v[174:177], v[182:185], v[32:35]
	s_waitcnt lgkmcnt(0)
	v_add_u32_e32 v235, 0x18000, v155
	v_add_u32_e32 v236, 0x18000, v156
	s_waitcnt vmcnt(0)
	s_barrier
	ds_read_b128 v[178:181], v235
	ds_read_b128 v[182:185], v235 offset:1024
	v_mfma_f32_16x16x32_bf16 v[28:31], v[158:161], v[186:189], v[28:31]
	v_mfma_f32_16x16x32_bf16 v[12:15], v[158:161], v[190:193], v[12:15]
	ds_read_b128 v[158:161], v236 offset:16384
	v_mfma_f32_16x16x32_bf16 v[24:27], v[162:165], v[186:189], v[24:27]
	v_mfma_f32_16x16x32_bf16 v[8:11], v[162:165], v[190:193], v[8:11]
	ds_read_b128 v[162:165], v236 offset:17408
	v_mfma_f32_16x16x32_bf16 v[20:23], v[170:173], v[186:189], v[20:23]
	v_mfma_f32_16x16x32_bf16 v[4:7], v[170:173], v[190:193], v[4:7]
	ds_read_b128 v[170:173], v236 offset:18432
	v_mfma_f32_16x16x32_bf16 v[16:19], v[174:177], v[186:189], v[16:19]
	v_mfma_f32_16x16x32_bf16 v[0:3], v[174:177], v[190:193], v[0:3]
	ds_read_b128 v[174:177], v236 offset:19456
	ds_read_b128 v[186:189], v235 offset:2048
	ds_read_b128 v[190:193], v235 offset:3072
	s_waitcnt lgkmcnt(5)
	v_mfma_f32_16x16x32_bf16 v[124:127], v[158:161], v[178:181], v[124:127]
	s_waitcnt lgkmcnt(4)
	v_mfma_f32_16x16x32_bf16 v[120:123], v[162:165], v[178:181], v[120:123]
	s_waitcnt lgkmcnt(3)
	v_mfma_f32_16x16x32_bf16 v[116:119], v[170:173], v[178:181], v[116:119]
	s_waitcnt lgkmcnt(2)
	v_mfma_f32_16x16x32_bf16 v[112:115], v[174:177], v[178:181], v[112:115]
	v_mfma_f32_16x16x32_bf16 v[108:111], v[158:161], v[182:185], v[108:111]
	v_mfma_f32_16x16x32_bf16 v[104:107], v[162:165], v[182:185], v[104:107]
	v_mfma_f32_16x16x32_bf16 v[100:103], v[170:173], v[182:185], v[100:103]
	v_mfma_f32_16x16x32_bf16 v[96:99], v[174:177], v[182:185], v[96:99]
	ds_read_b128 v[178:181], v235 offset:4096
	ds_read_b128 v[182:185], v235 offset:5120
	s_waitcnt lgkmcnt(3)
	v_mfma_f32_16x16x32_bf16 v[92:95], v[158:161], v[186:189], v[92:95]
	v_mfma_f32_16x16x32_bf16 v[88:91], v[162:165], v[186:189], v[88:91]
	v_mfma_f32_16x16x32_bf16 v[84:87], v[170:173], v[186:189], v[84:87]
	v_mfma_f32_16x16x32_bf16 v[80:83], v[174:177], v[186:189], v[80:83]
	s_waitcnt lgkmcnt(2)
	v_mfma_f32_16x16x32_bf16 v[76:79], v[158:161], v[190:193], v[76:79]
	v_mfma_f32_16x16x32_bf16 v[72:75], v[162:165], v[190:193], v[72:75]
	v_mfma_f32_16x16x32_bf16 v[68:71], v[170:173], v[190:193], v[68:71]
	v_mfma_f32_16x16x32_bf16 v[64:67], v[174:177], v[190:193], v[64:67]
	ds_read_b128 v[186:189], v235 offset:6144
	ds_read_b128 v[190:193], v235 offset:7168
	s_waitcnt lgkmcnt(3)
	v_mfma_f32_16x16x32_bf16 v[60:63], v[158:161], v[178:181], v[60:63]
	v_mfma_f32_16x16x32_bf16 v[56:59], v[162:165], v[178:181], v[56:59]
	v_mfma_f32_16x16x32_bf16 v[52:55], v[170:173], v[178:181], v[52:55]
	v_mfma_f32_16x16x32_bf16 v[48:51], v[174:177], v[178:181], v[48:51]
	s_waitcnt lgkmcnt(2)
	v_mfma_f32_16x16x32_bf16 v[44:47], v[158:161], v[182:185], v[44:47]
	v_mfma_f32_16x16x32_bf16 v[40:43], v[162:165], v[182:185], v[40:43]
	v_mfma_f32_16x16x32_bf16 v[36:39], v[170:173], v[182:185], v[36:39]
	v_mfma_f32_16x16x32_bf16 v[32:35], v[174:177], v[182:185], v[32:35]
	s_waitcnt lgkmcnt(0)
	v_mfma_f32_16x16x32_bf16 v[28:31], v[158:161], v[186:189], v[28:31]
	v_mfma_f32_16x16x32_bf16 v[12:15], v[158:161], v[190:193], v[12:15]
	v_mfma_f32_16x16x32_bf16 v[24:27], v[162:165], v[186:189], v[24:27]
	v_mfma_f32_16x16x32_bf16 v[8:11], v[162:165], v[190:193], v[8:11]
	v_mfma_f32_16x16x32_bf16 v[20:23], v[170:173], v[186:189], v[20:23]
	v_mfma_f32_16x16x32_bf16 v[4:7], v[170:173], v[190:193], v[4:7]
	v_mfma_f32_16x16x32_bf16 v[16:19], v[174:177], v[186:189], v[16:19]
	v_mfma_f32_16x16x32_bf16 v[0:3], v[174:177], v[190:193], v[0:3]
	s_nop 7

; __global__ void __launch_bounds__(NTHR) fwd_megakernel(Params p) {
;   extern __shared__ __attribute__((aligned(16))) char lds[];
	.amdhsa_kernel _Z14fwd_megakernel6Params
		.amdhsa_group_segment_fixed_size 0
		.amdhsa_private_segment_fixed_size 0
		.amdhsa_kernarg_size 496
		.amdhsa_user_sgpr_count 2
		.amdhsa_user_sgpr_dispatch_ptr 0
		.amdhsa_user_sgpr_queue_ptr 0
		.amdhsa_user_sgpr_kernarg_segment_ptr 1
		.amdhsa_user_sgpr_dispatch_id 0
		.amdhsa_user_sgpr_kernarg_preload_length 0
		.amdhsa_user_sgpr_kernarg_preload_offset 0
		.amdhsa_user_sgpr_private_segment_size 0
		.amdhsa_uses_dynamic_stack 0
		.amdhsa_enable_private_segment 0
		.amdhsa_system_sgpr_workgroup_id_x 1
		.amdhsa_system_sgpr_workgroup_id_y 0
		.amdhsa_system_sgpr_workgroup_id_z 0
		.amdhsa_system_sgpr_workgroup_info 0
		.amdhsa_system_vgpr_workitem_id 2
		.amdhsa_next_free_vgpr 240
		.amdhsa_next_free_sgpr 100
		.amdhsa_accum_offset 240
		.amdhsa_reserve_vcc 1
		.amdhsa_float_round_mode_32 0
		.amdhsa_float_round_mode_16_64 0
		.amdhsa_float_denorm_mode_32 3
		.amdhsa_float_denorm_mode_16_64 3
		.amdhsa_dx10_clamp 1
		.amdhsa_ieee_mode 1
		.amdhsa_fp16_overflow 0
		.amdhsa_tg_split 0
		.amdhsa_exception_fp_ieee_invalid_op 0
		.amdhsa_exception_fp_denorm_src 0
		.amdhsa_exception_fp_ieee_div_zero 0
		.amdhsa_exception_fp_ieee_overflow 0
		.amdhsa_exception_fp_ieee_underflow 0
		.amdhsa_exception_fp_ieee_inexact 0
		.amdhsa_exception_int_div_zero 0
	.end_amdhsa_kernel

; __global__ void __launch_bounds__(NTHR) fwd_megakernel(Params p) {
amdhsa.kernels:
  - .agpr_count:     0
    .args:
      - .offset:         0
        .size:           240
        .value_kind:     by_value
      - .offset:         240
        .size:           4
        .value_kind:     hidden_block_count_x
      - .offset:         244
        .size:           4
        .value_kind:     hidden_block_count_y
      - .offset:         248
        .size:           4
        .value_kind:     hidden_block_count_z
      - .offset:         252
        .size:           2
        .value_kind:     hidden_group_size_x
      - .offset:         254
        .size:           2
        .value_kind:     hidden_group_size_y
      - .offset:         256
        .size:           2
        .value_kind:     hidden_group_size_z
      - .offset:         258
        .size:           2
        .value_kind:     hidden_remainder_x
      - .offset:         260
        .size:           2
        .value_kind:     hidden_remainder_y
      - .offset:         262
        .size:           2
        .value_kind:     hidden_remainder_z
      - .offset:         280
        .size:           8
        .value_kind:     hidden_global_offset_x
      - .offset:         288
        .size:           8
        .value_kind:     hidden_global_offset_y
      - .offset:         296
        .size:           8
        .value_kind:     hidden_global_offset_z
      - .offset:         304
        .size:           2
        .value_kind:     hidden_grid_dims
      - .offset:         328
        .size:           8
        .value_kind:     hidden_multigrid_sync_arg
      - .offset:         360
        .size:           4
        .value_kind:     hidden_dynamic_lds_size
    .group_segment_fixed_size: 0
    .kernarg_segment_align: 8
    .kernarg_segment_size: 496
    .language:       OpenCL C
    .language_version:
      - 2
      - 0
    .max_flat_workgroup_size: 512
    .name:           _Z14fwd_megakernel6Params
    .private_segment_fixed_size: 0
    .sgpr_count:     106
    .sgpr_spill_count: 52
    .symbol:         _Z14fwd_megakernel6Params.kd
    .uniform_work_group_size: 1
    .uses_dynamic_stack: false
    .vgpr_count:     240
    .vgpr_spill_count: 0
    .wavefront_size: 64
